# v10: GLA scan work items remapped so the 8 value-column blocks of a recurrence chain run on one XCD (shared L2 lines for Qe/KdT)
# speedup vs baseline: 1.0576x; 1.0015x over previous
; __device__ __forceinline__ void ph_gla_scan(const Args& a, LAS unsigned char* lds) {
;     const int tid = threadIdx.x, lane = tid & 63, wave = __builtin_amdgcn_readfirstlane(tid >> 6), l16 = lane & 15, kg = lane >> 4;
;     const bf16* P = (const bf16*)(a.ws + WS_P);
;     const bf16* KDT = (const bf16*)(a.ws + WS_KDT); const bf16* PC = (const bf16*)(a.ws + WS_PC); const bf16* VT = (const bf16*)(a.ws + WS_VT); const float* ET = (const float*)(a.ws + WS_ET);
;     constexpr int QS = 528, RS = 144, L_K = 33792, L_V = 70656, L_P = 79872, L_E = 89088;
;     for (int item = blockIdx.x; item < 128; item += gridDim.x) {
;         const int chain = item >> 3, dvb = item & 7, b = chain >> 3, h = (chain >> 1) & 3, dir = chain & 1, bh = b * 4 + h;
;     ...
;         if (wave >= 4) {
;             const int ht = tid - 256;
;             v4u Qa[12], Qb[12], Ka[9], Kb[9];
.LBB0_295:
	s_cmp_lt_i32 s70, 5
	s_cselect_b64 s[2:3], -1, 0
	s_and_b64 s[6:7], s[2:3], s[0:1]
	s_andn2_b64 vcc, exec, s[6:7]
	s_cbranch_vccnz .LBB0_363
	s_cmpk_gt_i32 s95, 0x7f
	v_readfirstlane_b32 s0, v224
	s_cbranch_scc1 .LBB0_363
	s_add_u32 s22, s68, 0x25b00000
	s_addc_u32 s23, s69, 0
	s_add_u32 s24, s68, 0x2dd00000
	s_addc_u32 s25, s69, 0
	s_add_u32 s26, s68, 0x2ee00000
	s_addc_u32 s27, s69, 0
	s_cmpk_lt_u32 s0, 0x100
	v_add_u32_e32 v4, 0xffffff00, v224
	s_cselect_b64 s[8:9], -1, 0
	s_lshr_b32 s0, s0, 2
	v_lshlrev_b32_e32 v8, 2, v4
	v_lshlrev_b32_e32 v186, 4, v224
	v_and_b32_e32 v182, 15, v224
	s_and_b32 s4, s0, 48
	s_add_i32 s5, 0, 0x11400
	s_add_i32 s10, 0, 0x13800
	v_ashrrev_i32_e32 v9, 31, v8
	v_and_b32_e32 v5, 0x70, v186
	v_bfe_u32 v1, v224, 4, 2
	v_or_b32_e32 v0, s4, v182
	s_movk_i32 s0, 0x90
	v_mov_b32_e32 v2, s5
	s_movk_i32 s1, 0x210
	v_lshl_add_u64 v[8:9], v[8:9], 2, s[68:69]
	s_mov_b64 s[2:3], 0x3f200000
	v_add_u32_e32 v195, s5, v5
	v_add_u32_e32 v197, s10, v5
	v_add_u32_e32 v199, 0, v5
	v_ashrrev_i32_e32 v5, 31, v4
	v_mad_u32_u24 v3, v0, s0, v2
	v_lshlrev_b32_e32 v181, 4, v1
	v_mad_u32_u24 v183, v182, s1, 0
	v_lshlrev_b32_e32 v2, 2, v1
	v_mul_i32_i24_e32 v1, 0xfffffe80, v182
	v_lshl_add_u64 v[184:185], v[8:9], 0, s[2:3]
	v_lshlrev_b32_e32 v8, 4, v4
	v_ashrrev_i32_e32 v188, 5, v4
	v_lshlrev_b64 v[204:205], 4, v[4:5]
	v_lshrrev_b32_e32 v4, 3, v4
	v_add3_u32 v191, v183, v1, v181
	v_lshlrev_b32_e32 v1, 3, v224
	v_add_u32_e32 v9, 0x100, v224
	v_add_u32_e32 v10, 0x200, v224
	v_add_u32_e32 v11, 0x300, v224
	v_or_b32_e32 v12, 0x400, v224
	v_add_u32_e32 v13, 0x500, v224
	v_add_u32_e32 v14, 0x600, v224
	v_mul_i32_i24_e32 v225, 0x90, v4
	v_lshrrev_b32_e32 v4, 3, v224
	v_mov_b32_e32 v0, s10
	v_and_b32_e32 v6, 0xf8, v1
	v_and_b32_e32 v1, 0x1f0, v186
	v_lshrrev_b32_e32 v190, 5, v224
	v_lshrrev_b32_e32 v192, 5, v9
	v_lshrrev_b32_e32 v194, 5, v10
	v_lshrrev_b32_e32 v196, 5, v11
	v_lshrrev_b32_e32 v198, 5, v12
	v_lshrrev_b32_e32 v200, 5, v13
	v_lshrrev_b32_e32 v202, 5, v14
	v_lshlrev_b32_e32 v206, 4, v9
	v_lshlrev_b32_e32 v208, 4, v10
	v_lshlrev_b32_e32 v210, 4, v11
	v_lshlrev_b32_e32 v212, 4, v12
	v_lshlrev_b32_e32 v214, 4, v13
	v_mul_u32_u24_e32 v226, 0x90, v4
	v_lshrrev_b32_e32 v4, 3, v9
	v_lshrrev_b32_e32 v9, 3, v10
	v_lshrrev_b32_e32 v10, 3, v11
	v_lshrrev_b32_e32 v11, 3, v12
	v_lshrrev_b32_e32 v12, 3, v13
	v_lshrrev_b32_e32 v13, 3, v14
	v_mad_u32_u24 v7, v182, s0, v0
	v_mov_b32_e32 v0, 0
	s_movk_i32 s0, 0x140
	v_add_u32_e32 v1, 0, v1
	v_mul_i32_i24_e32 v5, 0x210, v188
	v_mul_u32_u24_e32 v15, 0x210, v190
	v_mul_u32_u24_e32 v16, 0x210, v192
	v_mul_u32_u24_e32 v17, 0x210, v194
	v_mul_u32_u24_e32 v18, 0x210, v196
	v_mul_u32_u24_e32 v19, 0x210, v198
	v_mul_u32_u24_e32 v20, 0x210, v200
	v_mul_u32_u24_e32 v21, 0x210, v202
	v_mul_u32_u24_e32 v4, 0x90, v4
	v_mul_u32_u24_e32 v9, 0x90, v9
	v_mul_u32_u24_e32 v10, 0x90, v10
	v_mul_u32_u24_e32 v11, 0x90, v11
	v_mul_u32_u24_e32 v12, 0x90, v12
	v_mul_u32_u24_e32 v13, 0x90, v13
	s_mov_b32 s11, 0
	v_add_u32_e32 v193, 0x8400, v191
	v_cmp_gt_u32_e64 s[0:1], s0, v224
	v_ashrrev_i32_e32 v189, 31, v188
	v_mov_b32_e32 v201, v0
	v_mov_b32_e32 v203, v0
	v_mov_b32_e32 v187, v0
	v_mov_b32_e32 v207, v0
	v_mov_b32_e32 v209, v0
	v_mov_b32_e32 v211, v0
	v_mov_b32_e32 v213, v0
	v_mov_b32_e32 v215, v0
	v_lshlrev_b32_e32 v216, 4, v14
	v_mov_b32_e32 v217, v0
	s_mov_b32 s28, 0x5300000
	s_lshl_b32 s29, s4, 1
	v_lshlrev_b32_e32 v218, 1, v2
	v_add_u32_e32 v227, v3, v181
	v_add_u32_e32 v228, v7, v181
	s_mov_b32 s30, 0x10000
	s_mov_b32 s31, 0x20000
	s_mov_b32 s33, 0x30000
	s_movk_i32 s34, 0x103
	v_lshlrev_b32_e32 v220, 1, v6
	s_movk_i32 s35, 0x3000
	v_mov_b32_e32 v229, 0x3000
	v_add_u32_e32 v230, v1, v5
	v_add_u32_e32 v231, v1, v15
	v_add_u32_e32 v232, v1, v16
	v_add_u32_e32 v233, v1, v17
	v_add_u32_e32 v234, v1, v18
	v_add_u32_e32 v235, v1, v19
	v_add_u32_e32 v236, v1, v20
	v_add_u32_e32 v237, v1, v21
	v_add_u32_e32 v238, v199, v4
	v_add_u32_e32 v239, v199, v9
	v_add_u32_e32 v240, v199, v10
	v_add_u32_e32 v241, v199, v11
	v_add_u32_e32 v242, v199, v12
	v_add_u32_e32 v243, v199, v13
	v_add_u32_e32 v244, 0, v8
	s_and_b32 s36, s95, 7
	s_lshl_b32 s36, s36, 3
	s_bfe_u32 s37, s95, 0x30003
	s_or_b32 s36, s36, s37
	s_and_b32 s37, s95, 0x40
	s_or_b32 s36, s36, s37
	s_branch .LBB0_299
